# GEMM K-loops: all load-segment trims together (SGPR-base DMAs, nop->ds_read, merged waits, scalar arithmetic hoisted into compute segments)
# speedup vs baseline: 1.0041x; 1.0041x over previous
.LBB0_120:
	ds_read_b128 v[130:133], v245
	ds_read_b128 v[134:137], v245 offset:1024
	ds_read_b128 v[138:141], v245 offset:2048
	ds_read_b128 v[142:145], v245 offset:3072
	s_waitcnt vmcnt(0)
	ds_read_b128 v[146:149], v246
	ds_read_b128 v[150:153], v246 offset:1024
	ds_read_b128 v[154:157], v246 offset:2048
	ds_read_b128 v[158:161], v246 offset:3072
	s_add_u32 s16, s6, 0xfffc0080
	s_addc_u32 s17, s7, -1
	s_cmp_eq_u32 s40, 12
	s_cselect_b32 s79, s1, s17
	s_cselect_b32 s78, s2, s16
	s_cselect_b32 s17, s3, s37
	s_cselect_b32 s16, s9, s35
	s_add_i32 m0, s71, 0xc000
	ds_read_b128 v[162:165], v247
	ds_read_b128 v[166:169], v247 offset:1024
	ds_read_b128 v[170:173], v247 offset:2048
	ds_read_b128 v[174:177], v247 offset:3072
	ds_read_b128 v[178:181], v247 offset:4096
	ds_read_b128 v[182:185], v247 offset:5120
	ds_read_b128 v[186:189], v247 offset:6144
	global_load_lds_dwordx4 v226, s[6:7]
	s_add_i32 m0, s71, 0xe000
	ds_read_b128 v[190:193], v247 offset:7168
	global_load_lds_dwordx4 v228, s[6:7]
	s_waitcnt vmcnt(8) lgkmcnt(0)
	s_barrier
	s_setprio 1
	v_mfma_f32_16x16x32_bf16 v[126:129], v[130:133], v[162:165], v[126:129]
	v_mfma_f32_16x16x32_bf16 v[122:125], v[138:141], v[162:165], v[122:125]
	v_mfma_f32_16x16x32_bf16 v[110:113], v[130:133], v[170:173], v[110:113]
	v_mfma_f32_16x16x32_bf16 v[106:109], v[138:141], v[170:173], v[106:109]
	v_mfma_f32_16x16x32_bf16 v[94:97], v[130:133], v[178:181], v[94:97]
	v_mfma_f32_16x16x32_bf16 v[90:93], v[138:141], v[178:181], v[90:93]
	v_mfma_f32_16x16x32_bf16 v[78:81], v[130:133], v[186:189], v[78:81]
	v_mfma_f32_16x16x32_bf16 v[74:77], v[138:141], v[186:189], v[74:77]
	v_mfma_f32_16x16x32_bf16 v[126:129], v[134:137], v[166:169], v[126:129]
	v_mfma_f32_16x16x32_bf16 v[122:125], v[142:145], v[166:169], v[122:125]
	v_mfma_f32_16x16x32_bf16 v[110:113], v[134:137], v[174:177], v[110:113]
	v_mfma_f32_16x16x32_bf16 v[106:109], v[142:145], v[174:177], v[106:109]
	v_mfma_f32_16x16x32_bf16 v[94:97], v[134:137], v[182:185], v[94:97]
	v_mfma_f32_16x16x32_bf16 v[90:93], v[142:145], v[182:185], v[90:93]
	v_mfma_f32_16x16x32_bf16 v[78:81], v[134:137], v[190:193], v[78:81]
	v_mfma_f32_16x16x32_bf16 v[74:77], v[142:145], v[190:193], v[74:77]
	s_setprio 0
	s_add_i32 s41, s12, s39
	s_add_u32 s42, s16, 0x40000
	s_addc_u32 s43, s17, 0
	s_setprio 1
	v_mfma_f32_16x16x32_bf16 v[118:121], v[146:149], v[162:165], v[118:121]
	v_mfma_f32_16x16x32_bf16 v[114:117], v[154:157], v[162:165], v[114:117]
	v_mfma_f32_16x16x32_bf16 v[102:105], v[146:149], v[170:173], v[102:105]
	v_mfma_f32_16x16x32_bf16 v[98:101], v[154:157], v[170:173], v[98:101]
	v_mfma_f32_16x16x32_bf16 v[86:89], v[146:149], v[178:181], v[86:89]
	v_mfma_f32_16x16x32_bf16 v[82:85], v[154:157], v[178:181], v[82:85]
	v_mfma_f32_16x16x32_bf16 v[70:73], v[146:149], v[186:189], v[70:73]
	v_mfma_f32_16x16x32_bf16 v[66:69], v[154:157], v[186:189], v[66:69]
	v_mfma_f32_16x16x32_bf16 v[118:121], v[150:153], v[166:169], v[118:121]
	v_mfma_f32_16x16x32_bf16 v[114:117], v[158:161], v[166:169], v[114:117]
	v_mfma_f32_16x16x32_bf16 v[102:105], v[150:153], v[174:177], v[102:105]
	v_mfma_f32_16x16x32_bf16 v[98:101], v[158:161], v[174:177], v[98:101]
	v_mfma_f32_16x16x32_bf16 v[86:89], v[150:153], v[182:185], v[86:89]
	v_mfma_f32_16x16x32_bf16 v[82:85], v[158:161], v[182:185], v[82:85]
	v_mfma_f32_16x16x32_bf16 v[70:73], v[150:153], v[190:193], v[70:73]
	v_mfma_f32_16x16x32_bf16 v[66:69], v[158:161], v[190:193], v[66:69]
	s_setprio 0
	s_barrier
	s_mov_b32 m0, s41
	ds_read_b128 v[162:165], v247 offset:16384
	ds_read_b128 v[166:169], v247 offset:17408
	ds_read_b128 v[170:173], v247 offset:18432
	ds_read_b128 v[174:177], v247 offset:19456
	global_load_lds_dwordx4 v212, s[16:17]
	s_add_i32 m0, s41, 0x2000
	s_add_i32 s41, s13, s39
	global_load_lds_dwordx4 v216, s[16:17]
	s_mov_b32 m0, s41
	ds_read_b128 v[190:193], v247 offset:23552
	global_load_lds_dwordx4 v212, s[42:43]
	s_add_i32 m0, s41, 0x2000
	ds_read_b128 v[186:189], v247 offset:22528
	global_load_lds_dwordx4 v216, s[42:43]
	s_mov_b32 m0, s71
	ds_read_b128 v[182:185], v247 offset:21504
	global_load_lds_dwordx4 v210, s[78:79]
	s_mov_b32 m0, s20
	ds_read_b128 v[178:181], v247 offset:20480
	global_load_lds_dwordx4 v214, s[78:79]
	s_waitcnt vmcnt(8) lgkmcnt(0)
	s_barrier
	s_setprio 1
	v_mfma_f32_16x16x32_bf16 v[62:65], v[130:133], v[162:165], v[62:65]
	v_mfma_f32_16x16x32_bf16 v[58:61], v[138:141], v[162:165], v[58:61]
	v_mfma_f32_16x16x32_bf16 v[46:49], v[130:133], v[170:173], v[46:49]
	v_mfma_f32_16x16x32_bf16 v[42:45], v[138:141], v[170:173], v[42:45]
	v_mfma_f32_16x16x32_bf16 v[30:33], v[130:133], v[178:181], v[30:33]
	v_mfma_f32_16x16x32_bf16 v[26:29], v[138:141], v[178:181], v[26:29]
	v_mfma_f32_16x16x32_bf16 v[14:17], v[130:133], v[186:189], v[14:17]
	v_mfma_f32_16x16x32_bf16 v[10:13], v[138:141], v[186:189], v[10:13]
	v_mfma_f32_16x16x32_bf16 v[62:65], v[134:137], v[166:169], v[62:65]
	v_mfma_f32_16x16x32_bf16 v[58:61], v[142:145], v[166:169], v[58:61]
	v_mfma_f32_16x16x32_bf16 v[46:49], v[134:137], v[174:177], v[46:49]
	v_mfma_f32_16x16x32_bf16 v[42:45], v[142:145], v[174:177], v[42:45]
	v_mfma_f32_16x16x32_bf16 v[30:33], v[134:137], v[182:185], v[30:33]
	v_mfma_f32_16x16x32_bf16 v[26:29], v[142:145], v[182:185], v[26:29]
	v_mfma_f32_16x16x32_bf16 v[14:17], v[134:137], v[190:193], v[14:17]
	v_mfma_f32_16x16x32_bf16 v[10:13], v[142:145], v[190:193], v[10:13]
	s_setprio 0
	s_add_i32 s41, 0, 0x18000
	s_add_i32 s44, 0, 0x1c000
	s_add_u32 s42, s78, 0x40000
	s_addc_u32 s43, s79, 0
	s_setprio 1
	v_mfma_f32_16x16x32_bf16 v[54:57], v[146:149], v[162:165], v[54:57]
	v_mfma_f32_16x16x32_bf16 v[50:53], v[154:157], v[162:165], v[50:53]
	v_mfma_f32_16x16x32_bf16 v[38:41], v[146:149], v[170:173], v[38:41]
	v_mfma_f32_16x16x32_bf16 v[34:37], v[154:157], v[170:173], v[34:37]
	v_mfma_f32_16x16x32_bf16 v[22:25], v[146:149], v[178:181], v[22:25]
	v_mfma_f32_16x16x32_bf16 v[18:21], v[154:157], v[178:181], v[18:21]
	v_mfma_f32_16x16x32_bf16 v[6:9], v[146:149], v[186:189], v[6:9]
	v_mfma_f32_16x16x32_bf16 v[2:5], v[154:157], v[186:189], v[2:5]
	v_mfma_f32_16x16x32_bf16 v[54:57], v[150:153], v[166:169], v[54:57]
	v_mfma_f32_16x16x32_bf16 v[50:53], v[158:161], v[166:169], v[50:53]
	v_mfma_f32_16x16x32_bf16 v[38:41], v[150:153], v[174:177], v[38:41]
	v_mfma_f32_16x16x32_bf16 v[34:37], v[158:161], v[174:177], v[34:37]
	v_mfma_f32_16x16x32_bf16 v[22:25], v[150:153], v[182:185], v[22:25]
	v_mfma_f32_16x16x32_bf16 v[18:21], v[158:161], v[182:185], v[18:21]
	v_mfma_f32_16x16x32_bf16 v[6:9], v[150:153], v[190:193], v[6:9]
	v_mfma_f32_16x16x32_bf16 v[2:5], v[158:161], v[190:193], v[2:5]
	s_setprio 0
	s_barrier
	v_add_u32_e32 v142, s41, v223
	v_add_u32_e32 v158, s44, v223
	ds_read_b128 v[130:133], v142
	ds_read_b128 v[134:137], v142 offset:1024
	ds_read_b128 v[138:141], v142 offset:2048
	ds_read_b128 v[142:145], v142 offset:3072
	ds_read_b128 v[146:149], v158
	ds_read_b128 v[150:153], v158 offset:1024
	ds_read_b128 v[154:157], v158 offset:2048
	ds_read_b128 v[158:161], v158 offset:3072
	s_mov_b32 m0, s21
	ds_read_b128 v[162:165], v247 offset:32768
	ds_read_b128 v[166:169], v247 offset:33792
	ds_read_b128 v[170:173], v247 offset:34816
	ds_read_b128 v[174:177], v247 offset:35840
	ds_read_b128 v[178:181], v247 offset:36864
	ds_read_b128 v[182:185], v247 offset:37888
	ds_read_b128 v[186:189], v247 offset:38912
	global_load_lds_dwordx4 v210, s[42:43]
	s_mov_b32 m0, s22
	ds_read_b128 v[190:193], v247 offset:39936
	global_load_lds_dwordx4 v214, s[42:43]
	s_waitcnt vmcnt(8) lgkmcnt(0)
	s_barrier
	s_setprio 1
	v_mfma_f32_16x16x32_bf16 v[126:129], v[130:133], v[162:165], v[126:129]
	v_mfma_f32_16x16x32_bf16 v[122:125], v[138:141], v[162:165], v[122:125]
	v_mfma_f32_16x16x32_bf16 v[110:113], v[130:133], v[170:173], v[110:113]
	v_mfma_f32_16x16x32_bf16 v[106:109], v[138:141], v[170:173], v[106:109]
	v_mfma_f32_16x16x32_bf16 v[94:97], v[130:133], v[178:181], v[94:97]
	v_mfma_f32_16x16x32_bf16 v[90:93], v[138:141], v[178:181], v[90:93]
	v_mfma_f32_16x16x32_bf16 v[78:81], v[130:133], v[186:189], v[78:81]
	v_mfma_f32_16x16x32_bf16 v[74:77], v[138:141], v[186:189], v[74:77]
	v_mfma_f32_16x16x32_bf16 v[126:129], v[134:137], v[166:169], v[126:129]
	v_mfma_f32_16x16x32_bf16 v[122:125], v[142:145], v[166:169], v[122:125]
	v_mfma_f32_16x16x32_bf16 v[110:113], v[134:137], v[174:177], v[110:113]
	v_mfma_f32_16x16x32_bf16 v[106:109], v[142:145], v[174:177], v[106:109]
	v_mfma_f32_16x16x32_bf16 v[94:97], v[134:137], v[182:185], v[94:97]
	v_mfma_f32_16x16x32_bf16 v[90:93], v[142:145], v[182:185], v[90:93]
	v_mfma_f32_16x16x32_bf16 v[78:81], v[134:137], v[190:193], v[78:81]
	v_mfma_f32_16x16x32_bf16 v[74:77], v[142:145], v[190:193], v[74:77]
	s_setprio 0
	s_add_i32 s41, s41, s39
	s_setprio 1
	v_mfma_f32_16x16x32_bf16 v[118:121], v[146:149], v[162:165], v[118:121]
	v_mfma_f32_16x16x32_bf16 v[114:117], v[154:157], v[162:165], v[114:117]
	v_mfma_f32_16x16x32_bf16 v[102:105], v[146:149], v[170:173], v[102:105]
	v_mfma_f32_16x16x32_bf16 v[98:101], v[154:157], v[170:173], v[98:101]
	v_mfma_f32_16x16x32_bf16 v[86:89], v[146:149], v[178:181], v[86:89]
	v_mfma_f32_16x16x32_bf16 v[82:85], v[154:157], v[178:181], v[82:85]
	v_mfma_f32_16x16x32_bf16 v[70:73], v[146:149], v[186:189], v[70:73]
	v_mfma_f32_16x16x32_bf16 v[66:69], v[154:157], v[186:189], v[66:69]
	v_mfma_f32_16x16x32_bf16 v[118:121], v[150:153], v[166:169], v[118:121]
	v_mfma_f32_16x16x32_bf16 v[114:117], v[158:161], v[166:169], v[114:117]
	v_mfma_f32_16x16x32_bf16 v[102:105], v[150:153], v[174:177], v[102:105]
	v_mfma_f32_16x16x32_bf16 v[98:101], v[158:161], v[174:177], v[98:101]
	v_mfma_f32_16x16x32_bf16 v[86:89], v[150:153], v[182:185], v[86:89]
	v_mfma_f32_16x16x32_bf16 v[82:85], v[158:161], v[182:185], v[82:85]
	v_mfma_f32_16x16x32_bf16 v[70:73], v[150:153], v[190:193], v[70:73]
	v_mfma_f32_16x16x32_bf16 v[66:69], v[158:161], v[190:193], v[66:69]
	s_setprio 0
	s_barrier
	s_add_i32 m0, s41, 0xffffff80
	ds_read_b128 v[162:165], v247 offset:49152
	ds_read_b128 v[166:169], v247 offset:50176
	ds_read_b128 v[170:173], v247 offset:51200
	ds_read_b128 v[174:177], v247 offset:52224
	global_load_lds_dwordx4 v212, s[16:17] offset:128
	s_add_i32 m0, s41, 0x1f80
	s_add_i32 s41, s44, s39
	global_load_lds_dwordx4 v216, s[16:17] offset:128
	s_add_u32 s16, s16, 0x40080
	s_addc_u32 s17, s17, 0
	s_mov_b32 m0, s41
	ds_read_b128 v[190:193], v247 offset:56320
	global_load_lds_dwordx4 v212, s[16:17]
	s_add_i32 m0, s41, 0x2000
	ds_read_b128 v[186:189], v247 offset:55296
	global_load_lds_dwordx4 v216, s[16:17]
	s_add_i32 m0, s14, 0xffffff80
	ds_read_b128 v[182:185], v247 offset:54272
	global_load_lds_dwordx4 v210, s[78:79] offset:128
	s_add_i32 m0, s15, 0xffffff80
	ds_read_b128 v[178:181], v247 offset:53248
	global_load_lds_dwordx4 v214, s[78:79] offset:128
	s_waitcnt vmcnt(8) lgkmcnt(0)
	s_barrier
	s_setprio 1
	v_mfma_f32_16x16x32_bf16 v[62:65], v[130:133], v[162:165], v[62:65]
	v_mfma_f32_16x16x32_bf16 v[58:61], v[138:141], v[162:165], v[58:61]
	v_mfma_f32_16x16x32_bf16 v[46:49], v[130:133], v[170:173], v[46:49]
	v_mfma_f32_16x16x32_bf16 v[42:45], v[138:141], v[170:173], v[42:45]
	v_mfma_f32_16x16x32_bf16 v[30:33], v[130:133], v[178:181], v[30:33]
	v_mfma_f32_16x16x32_bf16 v[26:29], v[138:141], v[178:181], v[26:29]
	v_mfma_f32_16x16x32_bf16 v[14:17], v[130:133], v[186:189], v[14:17]
	v_mfma_f32_16x16x32_bf16 v[10:13], v[138:141], v[186:189], v[10:13]
	v_mfma_f32_16x16x32_bf16 v[62:65], v[134:137], v[166:169], v[62:65]
	v_mfma_f32_16x16x32_bf16 v[58:61], v[142:145], v[166:169], v[58:61]
	v_mfma_f32_16x16x32_bf16 v[46:49], v[134:137], v[174:177], v[46:49]
	v_mfma_f32_16x16x32_bf16 v[42:45], v[142:145], v[174:177], v[42:45]
	v_mfma_f32_16x16x32_bf16 v[30:33], v[134:137], v[182:185], v[30:33]
	v_mfma_f32_16x16x32_bf16 v[26:29], v[142:145], v[182:185], v[26:29]
	v_mfma_f32_16x16x32_bf16 v[14:17], v[134:137], v[190:193], v[14:17]
	v_mfma_f32_16x16x32_bf16 v[10:13], v[142:145], v[190:193], v[10:13]
	s_setprio 0
	s_add_i32 s40, s40, 2
	s_add_u32 s6, s6, 0x100
	s_addc_u32 s7, s7, 0
	s_add_u32 s35, s35, 0x100
	s_addc_u32 s37, s37, 0
	s_setprio 1
	v_mfma_f32_16x16x32_bf16 v[54:57], v[146:149], v[162:165], v[54:57]
	v_mfma_f32_16x16x32_bf16 v[50:53], v[154:157], v[162:165], v[50:53]
	v_mfma_f32_16x16x32_bf16 v[38:41], v[146:149], v[170:173], v[38:41]
	v_mfma_f32_16x16x32_bf16 v[34:37], v[154:157], v[170:173], v[34:37]
	v_mfma_f32_16x16x32_bf16 v[22:25], v[146:149], v[178:181], v[22:25]
	v_mfma_f32_16x16x32_bf16 v[18:21], v[154:157], v[178:181], v[18:21]
	v_mfma_f32_16x16x32_bf16 v[6:9], v[146:149], v[186:189], v[6:9]
	v_mfma_f32_16x16x32_bf16 v[2:5], v[154:157], v[186:189], v[2:5]
	v_mfma_f32_16x16x32_bf16 v[54:57], v[150:153], v[166:169], v[54:57]
	v_mfma_f32_16x16x32_bf16 v[50:53], v[158:161], v[166:169], v[50:53]
	v_mfma_f32_16x16x32_bf16 v[38:41], v[150:153], v[174:177], v[38:41]
	v_mfma_f32_16x16x32_bf16 v[34:37], v[158:161], v[174:177], v[34:37]
	v_mfma_f32_16x16x32_bf16 v[22:25], v[150:153], v[182:185], v[22:25]
	v_mfma_f32_16x16x32_bf16 v[18:21], v[158:161], v[182:185], v[18:21]
	v_mfma_f32_16x16x32_bf16 v[6:9], v[150:153], v[190:193], v[6:9]
	v_mfma_f32_16x16x32_bf16 v[2:5], v[158:161], v[190:193], v[2:5]
	s_setprio 0
	s_barrier
	s_cmp_gt_u32 s40, 13
	s_cbranch_scc0 .LBB0_120
	s_and_b64 vcc, exec, s[48:49]
	s_cbranch_vccz .LBB0_123
	s_barrier

.LBB0_518:
	ds_read_b128 v[148:151], v143
	ds_read_b128 v[152:155], v143 offset:1024
	ds_read_b128 v[158:161], v143 offset:2048
	ds_read_b128 v[162:165], v143 offset:3072
	ds_read_b128 v[166:169], v144
	ds_read_b128 v[170:173], v144 offset:1024
	ds_read_b128 v[174:177], v144 offset:2048
	ds_read_b128 v[178:181], v144 offset:3072
	s_add_u32 s16, s8, s10
	s_addc_u32 s17, s9, s11
	s_add_u32 s16, s16, 0x1000100
	s_addc_u32 s17, s17, 0
	s_add_u32 s44, s30, s10
	s_addc_u32 s45, s31, s11
	s_cmpk_eq_i32 s10, 0x700
	s_cselect_b32 s29, s7, s17
	s_cselect_b32 s28, s6, s16
	s_cselect_b32 s17, s5, s45
	s_cselect_b32 s16, s4, s44
	s_mov_b32 m0, s34
	v_lshl_add_u64 v[214:215], v[138:139], 0, s[10:11]
	ds_read_b128 v[182:185], v145
	ds_read_b128 v[186:189], v145 offset:1024
	ds_read_b128 v[190:193], v145 offset:2048
	ds_read_b128 v[194:197], v145 offset:3072
	ds_read_b128 v[198:201], v145 offset:4096
	ds_read_b128 v[202:205], v145 offset:5120
	ds_read_b128 v[206:209], v145 offset:6144
	global_load_lds_dwordx4 v[214:215], off
	v_lshl_add_u64 v[214:215], v[140:141], 0, s[10:11]
	s_mov_b32 m0, s35
	ds_read_b128 v[210:213], v145 offset:7168
	global_load_lds_dwordx4 v[214:215], off
	s_waitcnt vmcnt(8) lgkmcnt(0)
	s_barrier
	s_setprio 1
	v_mfma_f32_16x16x32_bf16 v[126:129], v[148:151], v[182:185], v[126:129]
	v_mfma_f32_16x16x32_bf16 v[122:125], v[158:161], v[182:185], v[122:125]
	v_mfma_f32_16x16x32_bf16 v[110:113], v[148:151], v[190:193], v[110:113]
	v_mfma_f32_16x16x32_bf16 v[106:109], v[158:161], v[190:193], v[106:109]
	v_mfma_f32_16x16x32_bf16 v[94:97], v[148:151], v[198:201], v[94:97]
	v_mfma_f32_16x16x32_bf16 v[90:93], v[158:161], v[198:201], v[90:93]
	v_mfma_f32_16x16x32_bf16 v[78:81], v[148:151], v[206:209], v[78:81]
	v_mfma_f32_16x16x32_bf16 v[74:77], v[158:161], v[206:209], v[74:77]
	v_mfma_f32_16x16x32_bf16 v[126:129], v[152:155], v[186:189], v[126:129]
	v_mfma_f32_16x16x32_bf16 v[122:125], v[162:165], v[186:189], v[122:125]
	v_mfma_f32_16x16x32_bf16 v[110:113], v[152:155], v[194:197], v[110:113]
	v_mfma_f32_16x16x32_bf16 v[106:109], v[162:165], v[194:197], v[106:109]
	v_mfma_f32_16x16x32_bf16 v[94:97], v[152:155], v[202:205], v[94:97]
	v_mfma_f32_16x16x32_bf16 v[90:93], v[162:165], v[202:205], v[90:93]
	v_mfma_f32_16x16x32_bf16 v[78:81], v[152:155], v[210:213], v[78:81]
	v_mfma_f32_16x16x32_bf16 v[74:77], v[162:165], v[210:213], v[74:77]
	s_setprio 0
	s_add_u32 s44, s16, 0x40000
	s_addc_u32 s45, s17, 0
	s_setprio 1
	v_mfma_f32_16x16x32_bf16 v[118:121], v[166:169], v[182:185], v[118:121]
	v_mfma_f32_16x16x32_bf16 v[114:117], v[174:177], v[182:185], v[114:117]
	v_mfma_f32_16x16x32_bf16 v[102:105], v[166:169], v[190:193], v[102:105]
	v_mfma_f32_16x16x32_bf16 v[98:101], v[174:177], v[190:193], v[98:101]
	v_mfma_f32_16x16x32_bf16 v[86:89], v[166:169], v[198:201], v[86:89]
	v_mfma_f32_16x16x32_bf16 v[82:85], v[174:177], v[198:201], v[82:85]
	v_mfma_f32_16x16x32_bf16 v[70:73], v[166:169], v[206:209], v[70:73]
	v_mfma_f32_16x16x32_bf16 v[66:69], v[174:177], v[206:209], v[66:69]
	v_mfma_f32_16x16x32_bf16 v[118:121], v[170:173], v[186:189], v[118:121]
	v_mfma_f32_16x16x32_bf16 v[114:117], v[178:181], v[186:189], v[114:117]
	v_mfma_f32_16x16x32_bf16 v[102:105], v[170:173], v[194:197], v[102:105]
	v_mfma_f32_16x16x32_bf16 v[98:101], v[178:181], v[194:197], v[98:101]
	v_mfma_f32_16x16x32_bf16 v[86:89], v[170:173], v[202:205], v[86:89]
	v_mfma_f32_16x16x32_bf16 v[82:85], v[178:181], v[202:205], v[82:85]
	v_mfma_f32_16x16x32_bf16 v[70:73], v[170:173], v[210:213], v[70:73]
	v_mfma_f32_16x16x32_bf16 v[66:69], v[178:181], v[210:213], v[66:69]
	s_setprio 0
	s_barrier
	s_mov_b32 m0, s36
	v_lshl_add_u64 v[214:215], s[16:17], 0, v[132:133]
	ds_read_b128 v[182:185], v145 offset:16384
	ds_read_b128 v[186:189], v145 offset:17408
	ds_read_b128 v[190:193], v145 offset:18432
	ds_read_b128 v[194:197], v145 offset:19456
	ds_read_b128 v[198:201], v145 offset:20480
	global_load_lds_dwordx4 v132, s[16:17]
	v_lshl_add_u64 v[216:217], s[16:17], 0, v[136:137]
	s_mov_b32 m0, s37
	global_load_lds_dwordx4 v136, s[16:17]
	s_mov_b32 m0, s38
	v_lshl_add_u64 v[220:221], s[28:29], 0, v[134:135]
	global_load_lds_dwordx4 v132, s[44:45]
	s_mov_b32 m0, s39
	ds_read_b128 v[210:213], v145 offset:23552
	global_load_lds_dwordx4 v136, s[44:45]
	v_lshl_add_u64 v[218:219], s[28:29], 0, v[130:131]
	s_mov_b32 m0, s1
	ds_read_b128 v[206:209], v145 offset:22528
	global_load_lds_dwordx4 v130, s[28:29]
	s_mov_b32 m0, s15
	ds_read_b128 v[202:205], v145 offset:21504
	global_load_lds_dwordx4 v134, s[28:29]
	s_waitcnt vmcnt(8) lgkmcnt(0)
	s_barrier
	s_setprio 1
	v_mfma_f32_16x16x32_bf16 v[62:65], v[148:151], v[182:185], v[62:65]
	v_mfma_f32_16x16x32_bf16 v[58:61], v[158:161], v[182:185], v[58:61]
	v_mfma_f32_16x16x32_bf16 v[46:49], v[148:151], v[190:193], v[46:49]
	v_mfma_f32_16x16x32_bf16 v[42:45], v[158:161], v[190:193], v[42:45]
	v_mfma_f32_16x16x32_bf16 v[30:33], v[148:151], v[198:201], v[30:33]
	v_mfma_f32_16x16x32_bf16 v[26:29], v[158:161], v[198:201], v[26:29]
	v_mfma_f32_16x16x32_bf16 v[14:17], v[148:151], v[206:209], v[14:17]
	v_mfma_f32_16x16x32_bf16 v[10:13], v[158:161], v[206:209], v[10:13]
	v_mfma_f32_16x16x32_bf16 v[62:65], v[152:155], v[186:189], v[62:65]
	v_mfma_f32_16x16x32_bf16 v[58:61], v[162:165], v[186:189], v[58:61]
	v_mfma_f32_16x16x32_bf16 v[46:49], v[152:155], v[194:197], v[46:49]
	v_mfma_f32_16x16x32_bf16 v[42:45], v[162:165], v[194:197], v[42:45]
	v_mfma_f32_16x16x32_bf16 v[30:33], v[152:155], v[202:205], v[30:33]
	v_mfma_f32_16x16x32_bf16 v[26:29], v[162:165], v[202:205], v[26:29]
	v_mfma_f32_16x16x32_bf16 v[14:17], v[152:155], v[210:213], v[14:17]
	v_mfma_f32_16x16x32_bf16 v[10:13], v[162:165], v[210:213], v[10:13]
	s_setprio 0
	s_add_u32 s28, s28, 0x40000
	s_addc_u32 s29, s29, 0
	s_setprio 1
	v_mfma_f32_16x16x32_bf16 v[54:57], v[166:169], v[182:185], v[54:57]
	v_mfma_f32_16x16x32_bf16 v[50:53], v[174:177], v[182:185], v[50:53]
	v_mfma_f32_16x16x32_bf16 v[38:41], v[166:169], v[190:193], v[38:41]
	v_mfma_f32_16x16x32_bf16 v[34:37], v[174:177], v[190:193], v[34:37]
	v_mfma_f32_16x16x32_bf16 v[22:25], v[166:169], v[198:201], v[22:25]
	v_mfma_f32_16x16x32_bf16 v[18:21], v[174:177], v[198:201], v[18:21]
	v_mfma_f32_16x16x32_bf16 v[6:9], v[166:169], v[206:209], v[6:9]
	v_mfma_f32_16x16x32_bf16 v[2:5], v[174:177], v[206:209], v[2:5]
	v_mfma_f32_16x16x32_bf16 v[54:57], v[170:173], v[186:189], v[54:57]
	v_mfma_f32_16x16x32_bf16 v[50:53], v[178:181], v[186:189], v[50:53]
	v_mfma_f32_16x16x32_bf16 v[38:41], v[170:173], v[194:197], v[38:41]
	v_mfma_f32_16x16x32_bf16 v[34:37], v[178:181], v[194:197], v[34:37]
	v_mfma_f32_16x16x32_bf16 v[22:25], v[170:173], v[202:205], v[22:25]
	v_mfma_f32_16x16x32_bf16 v[18:21], v[178:181], v[202:205], v[18:21]
	v_mfma_f32_16x16x32_bf16 v[6:9], v[170:173], v[210:213], v[6:9]
	v_mfma_f32_16x16x32_bf16 v[2:5], v[178:181], v[210:213], v[2:5]
	s_setprio 0
	s_barrier
	ds_read_b128 v[148:151], v146
	ds_read_b128 v[152:155], v146 offset:1024
	ds_read_b128 v[158:161], v146 offset:2048
	ds_read_b128 v[162:165], v146 offset:3072
	ds_read_b128 v[166:169], v147
	ds_read_b128 v[170:173], v147 offset:1024
	ds_read_b128 v[174:177], v147 offset:2048
	ds_read_b128 v[178:181], v147 offset:3072
	s_mov_b32 m0, s20
	ds_read_b128 v[182:185], v145 offset:32768
	ds_read_b128 v[186:189], v145 offset:33792
	ds_read_b128 v[190:193], v145 offset:34816
	ds_read_b128 v[194:197], v145 offset:35840
	ds_read_b128 v[198:201], v145 offset:36864
	ds_read_b128 v[202:205], v145 offset:37888
	ds_read_b128 v[206:209], v145 offset:38912
	global_load_lds_dwordx4 v130, s[28:29]
	s_mov_b32 m0, s21
	ds_read_b128 v[210:213], v145 offset:39936
	global_load_lds_dwordx4 v134, s[28:29]
	s_waitcnt vmcnt(8) lgkmcnt(0)
	s_barrier
	s_setprio 1
	v_mfma_f32_16x16x32_bf16 v[126:129], v[148:151], v[182:185], v[126:129]
	v_mfma_f32_16x16x32_bf16 v[122:125], v[158:161], v[182:185], v[122:125]
	v_mfma_f32_16x16x32_bf16 v[110:113], v[148:151], v[190:193], v[110:113]
	v_mfma_f32_16x16x32_bf16 v[106:109], v[158:161], v[190:193], v[106:109]
	v_mfma_f32_16x16x32_bf16 v[94:97], v[148:151], v[198:201], v[94:97]
	v_mfma_f32_16x16x32_bf16 v[90:93], v[158:161], v[198:201], v[90:93]
	v_mfma_f32_16x16x32_bf16 v[78:81], v[148:151], v[206:209], v[78:81]
	v_mfma_f32_16x16x32_bf16 v[74:77], v[158:161], v[206:209], v[74:77]
	v_mfma_f32_16x16x32_bf16 v[126:129], v[152:155], v[186:189], v[126:129]
	v_mfma_f32_16x16x32_bf16 v[122:125], v[162:165], v[186:189], v[122:125]
	v_mfma_f32_16x16x32_bf16 v[110:113], v[152:155], v[194:197], v[110:113]
	v_mfma_f32_16x16x32_bf16 v[106:109], v[162:165], v[194:197], v[106:109]
	v_mfma_f32_16x16x32_bf16 v[94:97], v[152:155], v[202:205], v[94:97]
	v_mfma_f32_16x16x32_bf16 v[90:93], v[162:165], v[202:205], v[90:93]
	v_mfma_f32_16x16x32_bf16 v[78:81], v[152:155], v[210:213], v[78:81]
	v_mfma_f32_16x16x32_bf16 v[74:77], v[162:165], v[210:213], v[74:77]
	s_setprio 0
	s_add_u32 s16, s16, 0x40080
	s_addc_u32 s17, s17, 0
	s_setprio 1
	v_mfma_f32_16x16x32_bf16 v[118:121], v[166:169], v[182:185], v[118:121]
	v_mfma_f32_16x16x32_bf16 v[114:117], v[174:177], v[182:185], v[114:117]
	v_mfma_f32_16x16x32_bf16 v[102:105], v[166:169], v[190:193], v[102:105]
	v_mfma_f32_16x16x32_bf16 v[98:101], v[174:177], v[190:193], v[98:101]
	v_mfma_f32_16x16x32_bf16 v[86:89], v[166:169], v[198:201], v[86:89]
	v_mfma_f32_16x16x32_bf16 v[82:85], v[174:177], v[198:201], v[82:85]
	v_mfma_f32_16x16x32_bf16 v[70:73], v[166:169], v[206:209], v[70:73]
	v_mfma_f32_16x16x32_bf16 v[66:69], v[174:177], v[206:209], v[66:69]
	v_mfma_f32_16x16x32_bf16 v[118:121], v[170:173], v[186:189], v[118:121]
	v_mfma_f32_16x16x32_bf16 v[114:117], v[178:181], v[186:189], v[114:117]
	v_mfma_f32_16x16x32_bf16 v[102:105], v[170:173], v[194:197], v[102:105]
	v_mfma_f32_16x16x32_bf16 v[98:101], v[178:181], v[194:197], v[98:101]
	v_mfma_f32_16x16x32_bf16 v[86:89], v[170:173], v[202:205], v[86:89]
	v_mfma_f32_16x16x32_bf16 v[82:85], v[178:181], v[202:205], v[82:85]
	v_mfma_f32_16x16x32_bf16 v[70:73], v[170:173], v[210:213], v[70:73]
	v_mfma_f32_16x16x32_bf16 v[66:69], v[178:181], v[210:213], v[66:69]
	s_setprio 0
	s_barrier
	s_mov_b32 m0, s40
	v_lshl_add_u64 v[214:215], v[214:215], 0, s[2:3]
	ds_read_b128 v[182:185], v145 offset:49152
	ds_read_b128 v[186:189], v145 offset:50176
	ds_read_b128 v[190:193], v145 offset:51200
	ds_read_b128 v[194:197], v145 offset:52224
	global_load_lds_dwordx4 v[214:215], off
	v_lshl_add_u64 v[214:215], v[216:217], 0, s[2:3]
	s_mov_b32 m0, s41
	global_load_lds_dwordx4 v[214:215], off
	s_mov_b32 m0, s42
	ds_read_b128 v[210:213], v145 offset:56320
	global_load_lds_dwordx4 v132, s[16:17]
	s_mov_b32 m0, s43
	ds_read_b128 v[206:209], v145 offset:55296
	global_load_lds_dwordx4 v136, s[16:17]
	v_lshl_add_u64 v[214:215], v[218:219], 0, s[2:3]
	s_mov_b32 m0, s22
	ds_read_b128 v[202:205], v145 offset:54272
	global_load_lds_dwordx4 v[214:215], off
	v_lshl_add_u64 v[214:215], v[220:221], 0, s[2:3]
	s_mov_b32 m0, s23
	ds_read_b128 v[198:201], v145 offset:53248
	global_load_lds_dwordx4 v[214:215], off
	s_waitcnt vmcnt(8) lgkmcnt(0)
	s_barrier
	s_setprio 1
	v_mfma_f32_16x16x32_bf16 v[62:65], v[148:151], v[182:185], v[62:65]
	v_mfma_f32_16x16x32_bf16 v[58:61], v[158:161], v[182:185], v[58:61]
	v_mfma_f32_16x16x32_bf16 v[46:49], v[148:151], v[190:193], v[46:49]
	v_mfma_f32_16x16x32_bf16 v[42:45], v[158:161], v[190:193], v[42:45]
	v_mfma_f32_16x16x32_bf16 v[30:33], v[148:151], v[198:201], v[30:33]
	v_mfma_f32_16x16x32_bf16 v[26:29], v[158:161], v[198:201], v[26:29]
	v_mfma_f32_16x16x32_bf16 v[14:17], v[148:151], v[206:209], v[14:17]
	v_mfma_f32_16x16x32_bf16 v[10:13], v[158:161], v[206:209], v[10:13]
	v_mfma_f32_16x16x32_bf16 v[62:65], v[152:155], v[186:189], v[62:65]
	v_mfma_f32_16x16x32_bf16 v[58:61], v[162:165], v[186:189], v[58:61]
	v_mfma_f32_16x16x32_bf16 v[46:49], v[152:155], v[194:197], v[46:49]
	v_mfma_f32_16x16x32_bf16 v[42:45], v[162:165], v[194:197], v[42:45]
	v_mfma_f32_16x16x32_bf16 v[30:33], v[152:155], v[202:205], v[30:33]
	v_mfma_f32_16x16x32_bf16 v[26:29], v[162:165], v[202:205], v[26:29]
	v_mfma_f32_16x16x32_bf16 v[14:17], v[152:155], v[210:213], v[14:17]
	v_mfma_f32_16x16x32_bf16 v[10:13], v[162:165], v[210:213], v[10:13]
	s_setprio 0
	s_add_i32 s33, s33, 2
	s_add_u32 s10, s10, 0x100
	s_addc_u32 s11, s11, 0
	s_setprio 1
	v_mfma_f32_16x16x32_bf16 v[54:57], v[166:169], v[182:185], v[54:57]
	v_mfma_f32_16x16x32_bf16 v[50:53], v[174:177], v[182:185], v[50:53]
	v_mfma_f32_16x16x32_bf16 v[38:41], v[166:169], v[190:193], v[38:41]
	v_mfma_f32_16x16x32_bf16 v[34:37], v[174:177], v[190:193], v[34:37]
	v_mfma_f32_16x16x32_bf16 v[22:25], v[166:169], v[198:201], v[22:25]
	v_mfma_f32_16x16x32_bf16 v[18:21], v[174:177], v[198:201], v[18:21]
	v_mfma_f32_16x16x32_bf16 v[6:9], v[166:169], v[206:209], v[6:9]
	v_mfma_f32_16x16x32_bf16 v[2:5], v[174:177], v[206:209], v[2:5]
	v_mfma_f32_16x16x32_bf16 v[54:57], v[170:173], v[186:189], v[54:57]
	v_mfma_f32_16x16x32_bf16 v[50:53], v[178:181], v[186:189], v[50:53]
	v_mfma_f32_16x16x32_bf16 v[38:41], v[170:173], v[194:197], v[38:41]
	v_mfma_f32_16x16x32_bf16 v[34:37], v[178:181], v[194:197], v[34:37]
	v_mfma_f32_16x16x32_bf16 v[22:25], v[170:173], v[202:205], v[22:25]
	v_mfma_f32_16x16x32_bf16 v[18:21], v[178:181], v[202:205], v[18:21]
	v_mfma_f32_16x16x32_bf16 v[6:9], v[170:173], v[210:213], v[6:9]
	v_mfma_f32_16x16x32_bf16 v[2:5], v[178:181], v[210:213], v[2:5]
	s_setprio 0
	s_barrier
	s_cmp_gt_u32 s33, 13
	s_cbranch_scc0 .LBB0_518
	s_cmpk_lt_u32 s14, 0x100
	s_cbranch_scc0 .LBB0_521
	s_barrier

.LBB0_1250:
	ds_read_b128 v[146:149], v140
	ds_read_b128 v[150:153], v140 offset:1024
	ds_read_b128 v[154:157], v140 offset:2048
	ds_read_b128 v[158:161], v140 offset:3072
	ds_read_b128 v[162:165], v141
	ds_read_b128 v[166:169], v141 offset:1024
	ds_read_b128 v[170:173], v141 offset:2048
	ds_read_b128 v[174:177], v141 offset:3072
	s_add_u32 s14, s10, s12
	s_addc_u32 s15, s11, s13
	s_add_u32 s14, s14, 0x11400100
	s_addc_u32 s15, s15, 0
	s_add_u32 s39, s1, s12
	s_addc_u32 s40, s26, s13
	s_cmpk_eq_i32 s12, 0x700
	s_cselect_b32 s17, s9, s15
	s_cselect_b32 s16, s8, s14
	s_cselect_b32 s15, s7, s40
	s_cselect_b32 s14, s6, s39
	s_mov_b32 m0, s28
	v_lshl_add_u64 v[210:211], v[134:135], 0, s[12:13]
	ds_read_b128 v[178:181], v142
	ds_read_b128 v[182:185], v142 offset:1024
	ds_read_b128 v[186:189], v142 offset:2048
	ds_read_b128 v[190:193], v142 offset:3072
	ds_read_b128 v[194:197], v142 offset:4096
	ds_read_b128 v[198:201], v142 offset:5120
	ds_read_b128 v[202:205], v142 offset:6144
	global_load_lds_dwordx4 v[210:211], off
	v_lshl_add_u64 v[210:211], v[136:137], 0, s[12:13]
	s_mov_b32 m0, s29
	ds_read_b128 v[206:209], v142 offset:7168
	global_load_lds_dwordx4 v[210:211], off
	s_waitcnt vmcnt(8) lgkmcnt(0)
	s_barrier
	s_setprio 1
	v_mfma_f32_16x16x32_bf16 v[126:129], v[146:149], v[178:181], v[126:129]
	v_mfma_f32_16x16x32_bf16 v[122:125], v[154:157], v[178:181], v[122:125]
	v_mfma_f32_16x16x32_bf16 v[118:121], v[146:149], v[186:189], v[118:121]
	v_mfma_f32_16x16x32_bf16 v[114:117], v[154:157], v[186:189], v[114:117]
	v_mfma_f32_16x16x32_bf16 v[106:109], v[146:149], v[194:197], v[106:109]
	v_mfma_f32_16x16x32_bf16 v[98:101], v[154:157], v[194:197], v[98:101]
	v_mfma_f32_16x16x32_bf16 v[82:85], v[146:149], v[202:205], v[82:85]
	v_mfma_f32_16x16x32_bf16 v[74:77], v[154:157], v[202:205], v[74:77]
	v_mfma_f32_16x16x32_bf16 v[126:129], v[150:153], v[182:185], v[126:129]
	v_mfma_f32_16x16x32_bf16 v[122:125], v[158:161], v[182:185], v[122:125]
	v_mfma_f32_16x16x32_bf16 v[118:121], v[150:153], v[190:193], v[118:121]
	v_mfma_f32_16x16x32_bf16 v[114:117], v[158:161], v[190:193], v[114:117]
	v_mfma_f32_16x16x32_bf16 v[106:109], v[150:153], v[198:201], v[106:109]
	v_mfma_f32_16x16x32_bf16 v[98:101], v[158:161], v[198:201], v[98:101]
	v_mfma_f32_16x16x32_bf16 v[82:85], v[150:153], v[206:209], v[82:85]
	v_mfma_f32_16x16x32_bf16 v[74:77], v[158:161], v[206:209], v[74:77]
	s_setprio 0
	s_add_u32 s40, s14, 0x40000
	s_addc_u32 s41, s15, 0
	s_setprio 1
	v_mfma_f32_16x16x32_bf16 v[110:113], v[162:165], v[178:181], v[110:113]
	v_mfma_f32_16x16x32_bf16 v[102:105], v[170:173], v[178:181], v[102:105]
	v_mfma_f32_16x16x32_bf16 v[94:97], v[162:165], v[186:189], v[94:97]
	v_mfma_f32_16x16x32_bf16 v[90:93], v[170:173], v[186:189], v[90:93]
	v_mfma_f32_16x16x32_bf16 v[86:89], v[162:165], v[194:197], v[86:89]
	v_mfma_f32_16x16x32_bf16 v[78:81], v[170:173], v[194:197], v[78:81]
	v_mfma_f32_16x16x32_bf16 v[70:73], v[162:165], v[202:205], v[70:73]
	v_mfma_f32_16x16x32_bf16 v[66:69], v[170:173], v[202:205], v[66:69]
	v_mfma_f32_16x16x32_bf16 v[110:113], v[166:169], v[182:185], v[110:113]
	v_mfma_f32_16x16x32_bf16 v[102:105], v[174:177], v[182:185], v[102:105]
	v_mfma_f32_16x16x32_bf16 v[94:97], v[166:169], v[190:193], v[94:97]
	v_mfma_f32_16x16x32_bf16 v[90:93], v[174:177], v[190:193], v[90:93]
	v_mfma_f32_16x16x32_bf16 v[86:89], v[166:169], v[198:201], v[86:89]
	v_mfma_f32_16x16x32_bf16 v[78:81], v[174:177], v[198:201], v[78:81]
	v_mfma_f32_16x16x32_bf16 v[70:73], v[166:169], v[206:209], v[70:73]
	v_mfma_f32_16x16x32_bf16 v[66:69], v[174:177], v[206:209], v[66:69]
	s_setprio 0
	s_barrier
	s_mov_b32 m0, s30
	v_lshl_add_u64 v[210:211], s[14:15], 0, v[130:131]
	ds_read_b128 v[178:181], v142 offset:16384
	ds_read_b128 v[182:185], v142 offset:17408
	ds_read_b128 v[186:189], v142 offset:18432
	ds_read_b128 v[190:193], v142 offset:19456
	ds_read_b128 v[194:197], v142 offset:20480
	global_load_lds_dwordx4 v130, s[14:15]
	v_lshl_add_u64 v[212:213], s[14:15], 0, v[132:133]
	s_mov_b32 m0, s31
	global_load_lds_dwordx4 v132, s[14:15]
	s_mov_b32 m0, s33
	v_lshl_add_u64 v[216:217], s[16:17], 0, v[132:133]
	global_load_lds_dwordx4 v130, s[40:41]
	s_mov_b32 m0, s34
	ds_read_b128 v[206:209], v142 offset:23552
	global_load_lds_dwordx4 v132, s[40:41]
	v_lshl_add_u64 v[214:215], s[16:17], 0, v[130:131]
	s_mov_b32 m0, s5
	ds_read_b128 v[202:205], v142 offset:22528
	global_load_lds_dwordx4 v130, s[16:17]
	s_mov_b32 m0, s21
	ds_read_b128 v[198:201], v142 offset:21504
	global_load_lds_dwordx4 v132, s[16:17]
	s_waitcnt vmcnt(8) lgkmcnt(0)
	s_barrier
	s_setprio 1
	v_mfma_f32_16x16x32_bf16 v[62:65], v[146:149], v[178:181], v[62:65]
	v_mfma_f32_16x16x32_bf16 v[58:61], v[154:157], v[178:181], v[58:61]
	v_mfma_f32_16x16x32_bf16 v[54:57], v[146:149], v[186:189], v[54:57]
	v_mfma_f32_16x16x32_bf16 v[50:53], v[154:157], v[186:189], v[50:53]
	v_mfma_f32_16x16x32_bf16 v[34:37], v[146:149], v[194:197], v[34:37]
	v_mfma_f32_16x16x32_bf16 v[26:29], v[154:157], v[194:197], v[26:29]
	v_mfma_f32_16x16x32_bf16 v[22:25], v[146:149], v[202:205], v[22:25]
	v_mfma_f32_16x16x32_bf16 v[10:13], v[154:157], v[202:205], v[10:13]
	v_mfma_f32_16x16x32_bf16 v[62:65], v[150:153], v[182:185], v[62:65]
	v_mfma_f32_16x16x32_bf16 v[58:61], v[158:161], v[182:185], v[58:61]
	v_mfma_f32_16x16x32_bf16 v[54:57], v[150:153], v[190:193], v[54:57]
	v_mfma_f32_16x16x32_bf16 v[50:53], v[158:161], v[190:193], v[50:53]
	v_mfma_f32_16x16x32_bf16 v[34:37], v[150:153], v[198:201], v[34:37]
	v_mfma_f32_16x16x32_bf16 v[26:29], v[158:161], v[198:201], v[26:29]
	v_mfma_f32_16x16x32_bf16 v[22:25], v[150:153], v[206:209], v[22:25]
	v_mfma_f32_16x16x32_bf16 v[10:13], v[158:161], v[206:209], v[10:13]
	s_setprio 0
	s_add_u32 s16, s16, 0x40000
	s_addc_u32 s17, s17, 0
	s_setprio 1
	v_mfma_f32_16x16x32_bf16 v[46:49], v[162:165], v[178:181], v[46:49]
	v_mfma_f32_16x16x32_bf16 v[42:45], v[170:173], v[178:181], v[42:45]
	v_mfma_f32_16x16x32_bf16 v[38:41], v[162:165], v[186:189], v[38:41]
	v_mfma_f32_16x16x32_bf16 v[30:33], v[170:173], v[186:189], v[30:33]
	v_mfma_f32_16x16x32_bf16 v[18:21], v[162:165], v[194:197], v[18:21]
	v_mfma_f32_16x16x32_bf16 v[14:17], v[170:173], v[194:197], v[14:17]
	v_mfma_f32_16x16x32_bf16 v[6:9], v[162:165], v[202:205], v[6:9]
	v_mfma_f32_16x16x32_bf16 v[2:5], v[170:173], v[202:205], v[2:5]
	v_mfma_f32_16x16x32_bf16 v[46:49], v[166:169], v[182:185], v[46:49]
	v_mfma_f32_16x16x32_bf16 v[42:45], v[174:177], v[182:185], v[42:45]
	v_mfma_f32_16x16x32_bf16 v[38:41], v[166:169], v[190:193], v[38:41]
	v_mfma_f32_16x16x32_bf16 v[30:33], v[174:177], v[190:193], v[30:33]
	v_mfma_f32_16x16x32_bf16 v[18:21], v[166:169], v[198:201], v[18:21]
	v_mfma_f32_16x16x32_bf16 v[14:17], v[174:177], v[198:201], v[14:17]
	v_mfma_f32_16x16x32_bf16 v[6:9], v[166:169], v[206:209], v[6:9]
	v_mfma_f32_16x16x32_bf16 v[2:5], v[174:177], v[206:209], v[2:5]
	s_setprio 0
	s_barrier
	ds_read_b128 v[146:149], v143
	ds_read_b128 v[150:153], v143 offset:1024
	ds_read_b128 v[154:157], v143 offset:2048
	ds_read_b128 v[158:161], v143 offset:3072
	ds_read_b128 v[162:165], v144
	ds_read_b128 v[166:169], v144 offset:1024
	ds_read_b128 v[170:173], v144 offset:2048
	ds_read_b128 v[174:177], v144 offset:3072
	s_mov_b32 m0, s22
	ds_read_b128 v[178:181], v142 offset:32768
	ds_read_b128 v[182:185], v142 offset:33792
	ds_read_b128 v[186:189], v142 offset:34816
	ds_read_b128 v[190:193], v142 offset:35840
	ds_read_b128 v[194:197], v142 offset:36864
	ds_read_b128 v[198:201], v142 offset:37888
	ds_read_b128 v[202:205], v142 offset:38912
	global_load_lds_dwordx4 v130, s[16:17]
	s_mov_b32 m0, s23
	ds_read_b128 v[206:209], v142 offset:39936
	global_load_lds_dwordx4 v132, s[16:17]
	s_waitcnt vmcnt(8) lgkmcnt(0)
	s_barrier
	s_setprio 1
	v_mfma_f32_16x16x32_bf16 v[126:129], v[146:149], v[178:181], v[126:129]
	v_mfma_f32_16x16x32_bf16 v[122:125], v[154:157], v[178:181], v[122:125]
	v_mfma_f32_16x16x32_bf16 v[118:121], v[146:149], v[186:189], v[118:121]
	v_mfma_f32_16x16x32_bf16 v[114:117], v[154:157], v[186:189], v[114:117]
	v_mfma_f32_16x16x32_bf16 v[106:109], v[146:149], v[194:197], v[106:109]
	v_mfma_f32_16x16x32_bf16 v[98:101], v[154:157], v[194:197], v[98:101]
	v_mfma_f32_16x16x32_bf16 v[82:85], v[146:149], v[202:205], v[82:85]
	v_mfma_f32_16x16x32_bf16 v[74:77], v[154:157], v[202:205], v[74:77]
	v_mfma_f32_16x16x32_bf16 v[126:129], v[150:153], v[182:185], v[126:129]
	v_mfma_f32_16x16x32_bf16 v[122:125], v[158:161], v[182:185], v[122:125]
	v_mfma_f32_16x16x32_bf16 v[118:121], v[150:153], v[190:193], v[118:121]
	v_mfma_f32_16x16x32_bf16 v[114:117], v[158:161], v[190:193], v[114:117]
	v_mfma_f32_16x16x32_bf16 v[106:109], v[150:153], v[198:201], v[106:109]
	v_mfma_f32_16x16x32_bf16 v[98:101], v[158:161], v[198:201], v[98:101]
	v_mfma_f32_16x16x32_bf16 v[82:85], v[150:153], v[206:209], v[82:85]
	v_mfma_f32_16x16x32_bf16 v[74:77], v[158:161], v[206:209], v[74:77]
	s_setprio 0
	s_add_u32 s14, s14, 0x40080
	s_addc_u32 s15, s15, 0
	s_setprio 1
	v_mfma_f32_16x16x32_bf16 v[110:113], v[162:165], v[178:181], v[110:113]
	v_mfma_f32_16x16x32_bf16 v[102:105], v[170:173], v[178:181], v[102:105]
	v_mfma_f32_16x16x32_bf16 v[94:97], v[162:165], v[186:189], v[94:97]
	v_mfma_f32_16x16x32_bf16 v[90:93], v[170:173], v[186:189], v[90:93]
	v_mfma_f32_16x16x32_bf16 v[86:89], v[162:165], v[194:197], v[86:89]
	v_mfma_f32_16x16x32_bf16 v[78:81], v[170:173], v[194:197], v[78:81]
	v_mfma_f32_16x16x32_bf16 v[70:73], v[162:165], v[202:205], v[70:73]
	v_mfma_f32_16x16x32_bf16 v[66:69], v[170:173], v[202:205], v[66:69]
	v_mfma_f32_16x16x32_bf16 v[110:113], v[166:169], v[182:185], v[110:113]
	v_mfma_f32_16x16x32_bf16 v[102:105], v[174:177], v[182:185], v[102:105]
	v_mfma_f32_16x16x32_bf16 v[94:97], v[166:169], v[190:193], v[94:97]
	v_mfma_f32_16x16x32_bf16 v[90:93], v[174:177], v[190:193], v[90:93]
	v_mfma_f32_16x16x32_bf16 v[86:89], v[166:169], v[198:201], v[86:89]
	v_mfma_f32_16x16x32_bf16 v[78:81], v[174:177], v[198:201], v[78:81]
	v_mfma_f32_16x16x32_bf16 v[70:73], v[166:169], v[206:209], v[70:73]
	v_mfma_f32_16x16x32_bf16 v[66:69], v[174:177], v[206:209], v[66:69]
	s_setprio 0
	s_barrier
	s_mov_b32 m0, s35
	v_lshl_add_u64 v[210:211], v[210:211], 0, s[2:3]
	ds_read_b128 v[178:181], v142 offset:49152
	ds_read_b128 v[182:185], v142 offset:50176
	ds_read_b128 v[186:189], v142 offset:51200
	ds_read_b128 v[190:193], v142 offset:52224
	global_load_lds_dwordx4 v[210:211], off
	v_lshl_add_u64 v[210:211], v[212:213], 0, s[2:3]
	s_mov_b32 m0, s36
	global_load_lds_dwordx4 v[210:211], off
	s_mov_b32 m0, s37
	ds_read_b128 v[206:209], v142 offset:56320
	global_load_lds_dwordx4 v130, s[14:15]
	s_mov_b32 m0, s38
	ds_read_b128 v[202:205], v142 offset:55296
	global_load_lds_dwordx4 v132, s[14:15]
	v_lshl_add_u64 v[210:211], v[214:215], 0, s[2:3]
	s_mov_b32 m0, s24
	ds_read_b128 v[198:201], v142 offset:54272
	global_load_lds_dwordx4 v[210:211], off
	v_lshl_add_u64 v[210:211], v[216:217], 0, s[2:3]
	s_mov_b32 m0, s25
	ds_read_b128 v[194:197], v142 offset:53248
	global_load_lds_dwordx4 v[210:211], off
	s_waitcnt vmcnt(8) lgkmcnt(0)
	s_barrier
	s_setprio 1
	v_mfma_f32_16x16x32_bf16 v[62:65], v[146:149], v[178:181], v[62:65]
	v_mfma_f32_16x16x32_bf16 v[58:61], v[154:157], v[178:181], v[58:61]
	v_mfma_f32_16x16x32_bf16 v[54:57], v[146:149], v[186:189], v[54:57]
	v_mfma_f32_16x16x32_bf16 v[50:53], v[154:157], v[186:189], v[50:53]
	v_mfma_f32_16x16x32_bf16 v[34:37], v[146:149], v[194:197], v[34:37]
	v_mfma_f32_16x16x32_bf16 v[26:29], v[154:157], v[194:197], v[26:29]
	v_mfma_f32_16x16x32_bf16 v[22:25], v[146:149], v[202:205], v[22:25]
	v_mfma_f32_16x16x32_bf16 v[10:13], v[154:157], v[202:205], v[10:13]
	v_mfma_f32_16x16x32_bf16 v[62:65], v[150:153], v[182:185], v[62:65]
	v_mfma_f32_16x16x32_bf16 v[58:61], v[158:161], v[182:185], v[58:61]
	v_mfma_f32_16x16x32_bf16 v[54:57], v[150:153], v[190:193], v[54:57]
	v_mfma_f32_16x16x32_bf16 v[50:53], v[158:161], v[190:193], v[50:53]
	v_mfma_f32_16x16x32_bf16 v[34:37], v[150:153], v[198:201], v[34:37]
	v_mfma_f32_16x16x32_bf16 v[26:29], v[158:161], v[198:201], v[26:29]
	v_mfma_f32_16x16x32_bf16 v[22:25], v[150:153], v[206:209], v[22:25]
	v_mfma_f32_16x16x32_bf16 v[10:13], v[158:161], v[206:209], v[10:13]
	s_setprio 0
	s_add_i32 s27, s27, 2
	s_add_u32 s12, s12, 0x100
	s_addc_u32 s13, s13, 0
	s_setprio 1
	v_mfma_f32_16x16x32_bf16 v[46:49], v[162:165], v[178:181], v[46:49]
	v_mfma_f32_16x16x32_bf16 v[42:45], v[170:173], v[178:181], v[42:45]
	v_mfma_f32_16x16x32_bf16 v[38:41], v[162:165], v[186:189], v[38:41]
	v_mfma_f32_16x16x32_bf16 v[30:33], v[170:173], v[186:189], v[30:33]
	v_mfma_f32_16x16x32_bf16 v[18:21], v[162:165], v[194:197], v[18:21]
	v_mfma_f32_16x16x32_bf16 v[14:17], v[170:173], v[194:197], v[14:17]
	v_mfma_f32_16x16x32_bf16 v[6:9], v[162:165], v[202:205], v[6:9]
	v_mfma_f32_16x16x32_bf16 v[2:5], v[170:173], v[202:205], v[2:5]
	v_mfma_f32_16x16x32_bf16 v[46:49], v[166:169], v[182:185], v[46:49]
	v_mfma_f32_16x16x32_bf16 v[42:45], v[174:177], v[182:185], v[42:45]
	v_mfma_f32_16x16x32_bf16 v[38:41], v[166:169], v[190:193], v[38:41]
	v_mfma_f32_16x16x32_bf16 v[30:33], v[174:177], v[190:193], v[30:33]
	v_mfma_f32_16x16x32_bf16 v[18:21], v[166:169], v[198:201], v[18:21]
	v_mfma_f32_16x16x32_bf16 v[14:17], v[174:177], v[198:201], v[14:17]
	v_mfma_f32_16x16x32_bf16 v[6:9], v[166:169], v[206:209], v[6:9]
	v_mfma_f32_16x16x32_bf16 v[2:5], v[174:177], v[206:209], v[2:5]
	s_setprio 0
	s_barrier
	s_cmp_gt_u32 s27, 13
	s_cbranch_scc0 .LBB0_1250
	s_cmpk_lt_u32 s19, 0x100
	s_cbranch_scc0 .LBB0_1253
	s_barrier

.LBB0_1381:
	ds_read_b128 v[138:141], v147
	ds_read_b128 v[150:153], v147 offset:1024
	ds_read_b128 v[154:157], v147 offset:2048
	ds_read_b128 v[158:161], v147 offset:3072
	ds_read_b128 v[162:165], v148
	ds_read_b128 v[166:169], v148 offset:1024
	ds_read_b128 v[170:173], v148 offset:2048
	ds_read_b128 v[174:177], v148 offset:3072
	s_add_u32 s24, s2, 0xfffc0080
	s_addc_u32 s25, s3, -1
	s_cmp_eq_u32 s53, 12
	s_cselect_b32 s27, s17, s25
	s_cselect_b32 s26, s49, s24
	s_cselect_b32 s25, s15, s52
	s_cselect_b32 s24, s50, s51
	s_add_i32 m0, s23, 0xc000
	ds_read_b128 v[178:181], v149
	ds_read_b128 v[182:185], v149 offset:1024
	ds_read_b128 v[186:189], v149 offset:2048
	ds_read_b128 v[190:193], v149 offset:3072
	ds_read_b128 v[194:197], v149 offset:4096
	ds_read_b128 v[198:201], v149 offset:5120
	ds_read_b128 v[202:205], v149 offset:6144
	global_load_lds_dwordx4 v132, s[2:3]
	s_add_i32 m0, s23, 0xe000
	ds_read_b128 v[206:209], v149 offset:7168
	global_load_lds_dwordx4 v134, s[2:3]
	s_waitcnt vmcnt(8) lgkmcnt(0)
	s_barrier
	s_setprio 1
	v_mfma_f32_16x16x32_bf16 v[124:127], v[138:141], v[178:181], v[124:127]
	v_mfma_f32_16x16x32_bf16 v[120:123], v[154:157], v[178:181], v[120:123]
	v_mfma_f32_16x16x32_bf16 v[116:119], v[138:141], v[186:189], v[116:119]
	v_mfma_f32_16x16x32_bf16 v[112:115], v[154:157], v[186:189], v[112:115]
	v_mfma_f32_16x16x32_bf16 v[104:107], v[138:141], v[194:197], v[104:107]
	v_mfma_f32_16x16x32_bf16 v[96:99], v[154:157], v[194:197], v[96:99]
	v_mfma_f32_16x16x32_bf16 v[88:91], v[138:141], v[202:205], v[88:91]
	v_mfma_f32_16x16x32_bf16 v[80:83], v[154:157], v[202:205], v[80:83]
	v_mfma_f32_16x16x32_bf16 v[124:127], v[150:153], v[182:185], v[124:127]
	v_mfma_f32_16x16x32_bf16 v[120:123], v[158:161], v[182:185], v[120:123]
	v_mfma_f32_16x16x32_bf16 v[116:119], v[150:153], v[190:193], v[116:119]
	v_mfma_f32_16x16x32_bf16 v[112:115], v[158:161], v[190:193], v[112:115]
	v_mfma_f32_16x16x32_bf16 v[104:107], v[150:153], v[198:201], v[104:107]
	v_mfma_f32_16x16x32_bf16 v[96:99], v[158:161], v[198:201], v[96:99]
	v_mfma_f32_16x16x32_bf16 v[88:91], v[150:153], v[206:209], v[88:91]
	v_mfma_f32_16x16x32_bf16 v[80:83], v[158:161], v[206:209], v[80:83]
	s_setprio 0
	s_add_i32 s54, s4, s29
	s_add_i32 s56, s41, s29
	s_setprio 1
	v_mfma_f32_16x16x32_bf16 v[108:111], v[162:165], v[178:181], v[108:111]
	v_mfma_f32_16x16x32_bf16 v[100:103], v[170:173], v[178:181], v[100:103]
	v_mfma_f32_16x16x32_bf16 v[92:95], v[162:165], v[186:189], v[92:95]
	v_mfma_f32_16x16x32_bf16 v[84:87], v[170:173], v[186:189], v[84:87]
	v_mfma_f32_16x16x32_bf16 v[76:79], v[162:165], v[194:197], v[76:79]
	v_mfma_f32_16x16x32_bf16 v[72:75], v[170:173], v[194:197], v[72:75]
	v_mfma_f32_16x16x32_bf16 v[68:71], v[162:165], v[202:205], v[68:71]
	v_mfma_f32_16x16x32_bf16 v[64:67], v[170:173], v[202:205], v[64:67]
	v_mfma_f32_16x16x32_bf16 v[108:111], v[166:169], v[182:185], v[108:111]
	v_mfma_f32_16x16x32_bf16 v[100:103], v[174:177], v[182:185], v[100:103]
	v_mfma_f32_16x16x32_bf16 v[92:95], v[166:169], v[190:193], v[92:95]
	v_mfma_f32_16x16x32_bf16 v[84:87], v[174:177], v[190:193], v[84:87]
	v_mfma_f32_16x16x32_bf16 v[76:79], v[166:169], v[198:201], v[76:79]
	v_mfma_f32_16x16x32_bf16 v[72:75], v[174:177], v[198:201], v[72:75]
	v_mfma_f32_16x16x32_bf16 v[68:71], v[166:169], v[206:209], v[68:71]
	v_mfma_f32_16x16x32_bf16 v[64:67], v[174:177], v[206:209], v[64:67]
	s_setprio 0
	s_barrier
	s_mov_b32 m0, s54
	ds_read_b128 v[178:181], v149 offset:16384
	ds_read_b128 v[182:185], v149 offset:17408
	ds_read_b128 v[186:189], v149 offset:18432
	ds_read_b128 v[190:193], v149 offset:19456
	ds_read_b128 v[194:197], v149 offset:20480
	global_load_lds_dwordx4 v130, s[24:25]
	s_add_i32 m0, s54, 0x2000
	s_add_u32 s54, s24, 0x40000
	s_addc_u32 s55, s25, 0
	global_load_lds_dwordx4 v128, s[24:25]
	s_mov_b32 m0, s56
	v_lshl_add_u64 v[214:215], s[26:27], 0, v[128:129]
	global_load_lds_dwordx4 v130, s[54:55]
	s_add_i32 m0, s56, 0x2000
	ds_read_b128 v[206:209], v149 offset:23552
	global_load_lds_dwordx4 v128, s[54:55]
	v_lshl_add_u64 v[212:213], s[26:27], 0, v[130:131]
	s_mov_b32 m0, s23
	ds_read_b128 v[202:205], v149 offset:22528
	global_load_lds_dwordx4 v130, s[26:27]
	s_mov_b32 m0, s34
	ds_read_b128 v[198:201], v149 offset:21504
	global_load_lds_dwordx4 v128, s[26:27]
	s_waitcnt vmcnt(8) lgkmcnt(0)
	s_barrier
	s_setprio 1
	v_mfma_f32_16x16x32_bf16 v[60:63], v[138:141], v[178:181], v[60:63]
	v_mfma_f32_16x16x32_bf16 v[56:59], v[154:157], v[178:181], v[56:59]
	v_mfma_f32_16x16x32_bf16 v[52:55], v[138:141], v[186:189], v[52:55]
	v_mfma_f32_16x16x32_bf16 v[48:51], v[154:157], v[186:189], v[48:51]
	v_mfma_f32_16x16x32_bf16 v[44:47], v[138:141], v[194:197], v[44:47]
	v_mfma_f32_16x16x32_bf16 v[32:35], v[154:157], v[194:197], v[32:35]
	v_mfma_f32_16x16x32_bf16 v[20:23], v[138:141], v[202:205], v[20:23]
	v_mfma_f32_16x16x32_bf16 v[8:11], v[154:157], v[202:205], v[8:11]
	v_mfma_f32_16x16x32_bf16 v[60:63], v[150:153], v[182:185], v[60:63]
	v_mfma_f32_16x16x32_bf16 v[56:59], v[158:161], v[182:185], v[56:59]
	v_mfma_f32_16x16x32_bf16 v[52:55], v[150:153], v[190:193], v[52:55]
	v_mfma_f32_16x16x32_bf16 v[48:51], v[158:161], v[190:193], v[48:51]
	v_mfma_f32_16x16x32_bf16 v[44:47], v[150:153], v[198:201], v[44:47]
	v_mfma_f32_16x16x32_bf16 v[32:35], v[158:161], v[198:201], v[32:35]
	v_mfma_f32_16x16x32_bf16 v[20:23], v[150:153], v[206:209], v[20:23]
	v_mfma_f32_16x16x32_bf16 v[8:11], v[158:161], v[206:209], v[8:11]
	s_setprio 0
	s_add_i32 s54, 0, 0x18000
	s_add_i32 s55, 0, 0x1c000
	s_add_u32 s26, s26, 0x40000
	s_addc_u32 s27, s27, 0
	s_setprio 1
	v_mfma_f32_16x16x32_bf16 v[40:43], v[162:165], v[178:181], v[40:43]
	v_mfma_f32_16x16x32_bf16 v[36:39], v[170:173], v[178:181], v[36:39]
	v_mfma_f32_16x16x32_bf16 v[28:31], v[162:165], v[186:189], v[28:31]
	v_mfma_f32_16x16x32_bf16 v[24:27], v[170:173], v[186:189], v[24:27]
	v_mfma_f32_16x16x32_bf16 v[16:19], v[162:165], v[194:197], v[16:19]
	v_mfma_f32_16x16x32_bf16 v[12:15], v[170:173], v[194:197], v[12:15]
	v_mfma_f32_16x16x32_bf16 v[4:7], v[162:165], v[202:205], v[4:7]
	v_mfma_f32_16x16x32_bf16 v[0:3], v[170:173], v[202:205], v[0:3]
	v_mfma_f32_16x16x32_bf16 v[40:43], v[166:169], v[182:185], v[40:43]
	v_mfma_f32_16x16x32_bf16 v[36:39], v[174:177], v[182:185], v[36:39]
	v_mfma_f32_16x16x32_bf16 v[28:31], v[166:169], v[190:193], v[28:31]
	v_mfma_f32_16x16x32_bf16 v[24:27], v[174:177], v[190:193], v[24:27]
	v_mfma_f32_16x16x32_bf16 v[16:19], v[166:169], v[198:201], v[16:19]
	v_mfma_f32_16x16x32_bf16 v[12:15], v[174:177], v[198:201], v[12:15]
	v_mfma_f32_16x16x32_bf16 v[4:7], v[166:169], v[206:209], v[4:7]
	v_mfma_f32_16x16x32_bf16 v[0:3], v[174:177], v[206:209], v[0:3]
	s_setprio 0
	s_barrier
	v_add_u32_e32 v158, s54, v145
	v_add_u32_e32 v174, s55, v145
	ds_read_b128 v[138:141], v158
	ds_read_b128 v[150:153], v158 offset:1024
	ds_read_b128 v[154:157], v158 offset:2048
	ds_read_b128 v[158:161], v158 offset:3072
	ds_read_b128 v[162:165], v174
	ds_read_b128 v[166:169], v174 offset:1024
	ds_read_b128 v[170:173], v174 offset:2048
	ds_read_b128 v[174:177], v174 offset:3072
	s_mov_b32 m0, s35
	ds_read_b128 v[178:181], v149 offset:32768
	ds_read_b128 v[182:185], v149 offset:33792
	ds_read_b128 v[186:189], v149 offset:34816
	ds_read_b128 v[190:193], v149 offset:35840
	ds_read_b128 v[194:197], v149 offset:36864
	ds_read_b128 v[198:201], v149 offset:37888
	ds_read_b128 v[202:205], v149 offset:38912
	global_load_lds_dwordx4 v130, s[26:27]
	s_mov_b32 m0, s36
	ds_read_b128 v[206:209], v149 offset:39936
	global_load_lds_dwordx4 v128, s[26:27]
	s_waitcnt vmcnt(8) lgkmcnt(0)
	s_barrier
	s_setprio 1
	v_mfma_f32_16x16x32_bf16 v[124:127], v[138:141], v[178:181], v[124:127]
	v_mfma_f32_16x16x32_bf16 v[120:123], v[154:157], v[178:181], v[120:123]
	v_mfma_f32_16x16x32_bf16 v[116:119], v[138:141], v[186:189], v[116:119]
	v_mfma_f32_16x16x32_bf16 v[112:115], v[154:157], v[186:189], v[112:115]
	v_mfma_f32_16x16x32_bf16 v[104:107], v[138:141], v[194:197], v[104:107]
	v_mfma_f32_16x16x32_bf16 v[96:99], v[154:157], v[194:197], v[96:99]
	v_mfma_f32_16x16x32_bf16 v[88:91], v[138:141], v[202:205], v[88:91]
	v_mfma_f32_16x16x32_bf16 v[80:83], v[154:157], v[202:205], v[80:83]
	v_mfma_f32_16x16x32_bf16 v[124:127], v[150:153], v[182:185], v[124:127]
	v_mfma_f32_16x16x32_bf16 v[120:123], v[158:161], v[182:185], v[120:123]
	v_mfma_f32_16x16x32_bf16 v[116:119], v[150:153], v[190:193], v[116:119]
	v_mfma_f32_16x16x32_bf16 v[112:115], v[158:161], v[190:193], v[112:115]
	v_mfma_f32_16x16x32_bf16 v[104:107], v[150:153], v[198:201], v[104:107]
	v_mfma_f32_16x16x32_bf16 v[96:99], v[158:161], v[198:201], v[96:99]
	v_mfma_f32_16x16x32_bf16 v[88:91], v[150:153], v[206:209], v[88:91]
	v_mfma_f32_16x16x32_bf16 v[80:83], v[158:161], v[206:209], v[80:83]
	s_setprio 0
	s_add_i32 s26, s54, s29
	s_setprio 1
	v_mfma_f32_16x16x32_bf16 v[108:111], v[162:165], v[178:181], v[108:111]
	v_mfma_f32_16x16x32_bf16 v[100:103], v[170:173], v[178:181], v[100:103]
	v_mfma_f32_16x16x32_bf16 v[92:95], v[162:165], v[186:189], v[92:95]
	v_mfma_f32_16x16x32_bf16 v[84:87], v[170:173], v[186:189], v[84:87]
	v_mfma_f32_16x16x32_bf16 v[76:79], v[162:165], v[194:197], v[76:79]
	v_mfma_f32_16x16x32_bf16 v[72:75], v[170:173], v[194:197], v[72:75]
	v_mfma_f32_16x16x32_bf16 v[68:71], v[162:165], v[202:205], v[68:71]
	v_mfma_f32_16x16x32_bf16 v[64:67], v[170:173], v[202:205], v[64:67]
	v_mfma_f32_16x16x32_bf16 v[108:111], v[166:169], v[182:185], v[108:111]
	v_mfma_f32_16x16x32_bf16 v[100:103], v[174:177], v[182:185], v[100:103]
	v_mfma_f32_16x16x32_bf16 v[92:95], v[166:169], v[190:193], v[92:95]
	v_mfma_f32_16x16x32_bf16 v[84:87], v[174:177], v[190:193], v[84:87]
	v_mfma_f32_16x16x32_bf16 v[76:79], v[166:169], v[198:201], v[76:79]
	v_mfma_f32_16x16x32_bf16 v[72:75], v[174:177], v[198:201], v[72:75]
	v_mfma_f32_16x16x32_bf16 v[68:71], v[166:169], v[206:209], v[68:71]
	v_mfma_f32_16x16x32_bf16 v[64:67], v[174:177], v[206:209], v[64:67]
	s_setprio 0
	s_barrier
	s_add_i32 m0, s26, 0xffffff80
	ds_read_b128 v[178:181], v149 offset:49152
	ds_read_b128 v[182:185], v149 offset:50176
	ds_read_b128 v[186:189], v149 offset:51200
	ds_read_b128 v[190:193], v149 offset:52224
	global_load_lds_dwordx4 v130, s[24:25] offset:128
	s_add_i32 m0, s26, 0x1f80
	s_add_i32 s26, s55, s29
	global_load_lds_dwordx4 v128, s[24:25] offset:128
	s_add_u32 s24, s24, 0x40080
	s_addc_u32 s25, s25, 0
	s_mov_b32 m0, s26
	ds_read_b128 v[206:209], v149 offset:56320
	global_load_lds_dwordx4 v130, s[24:25]
	s_add_i32 m0, s26, 0x2000
	ds_read_b128 v[202:205], v149 offset:55296
	global_load_lds_dwordx4 v128, s[24:25]
	v_lshl_add_u64 v[142:143], v[212:213], 0, s[8:9]
	s_mov_b32 m0, s38
	ds_read_b128 v[198:201], v149 offset:54272
	global_load_lds_dwordx4 v[142:143], off
	v_lshl_add_u64 v[142:143], v[214:215], 0, s[8:9]
	s_mov_b32 m0, s39
	ds_read_b128 v[194:197], v149 offset:53248
	global_load_lds_dwordx4 v[142:143], off
	s_waitcnt vmcnt(8) lgkmcnt(0)
	s_barrier
	s_setprio 1
	v_mfma_f32_16x16x32_bf16 v[60:63], v[138:141], v[178:181], v[60:63]
	v_mfma_f32_16x16x32_bf16 v[56:59], v[154:157], v[178:181], v[56:59]
	v_mfma_f32_16x16x32_bf16 v[52:55], v[138:141], v[186:189], v[52:55]
	v_mfma_f32_16x16x32_bf16 v[48:51], v[154:157], v[186:189], v[48:51]
	v_mfma_f32_16x16x32_bf16 v[44:47], v[138:141], v[194:197], v[44:47]
	v_mfma_f32_16x16x32_bf16 v[32:35], v[154:157], v[194:197], v[32:35]
	v_mfma_f32_16x16x32_bf16 v[20:23], v[138:141], v[202:205], v[20:23]
	v_mfma_f32_16x16x32_bf16 v[8:11], v[154:157], v[202:205], v[8:11]
	v_mfma_f32_16x16x32_bf16 v[60:63], v[150:153], v[182:185], v[60:63]
	v_mfma_f32_16x16x32_bf16 v[56:59], v[158:161], v[182:185], v[56:59]
	v_mfma_f32_16x16x32_bf16 v[52:55], v[150:153], v[190:193], v[52:55]
	v_mfma_f32_16x16x32_bf16 v[48:51], v[158:161], v[190:193], v[48:51]
	v_mfma_f32_16x16x32_bf16 v[44:47], v[150:153], v[198:201], v[44:47]
	v_mfma_f32_16x16x32_bf16 v[32:35], v[158:161], v[198:201], v[32:35]
	v_mfma_f32_16x16x32_bf16 v[20:23], v[150:153], v[206:209], v[20:23]
	v_mfma_f32_16x16x32_bf16 v[8:11], v[158:161], v[206:209], v[8:11]
	s_setprio 0
	s_add_i32 s53, s53, 2
	s_add_u32 s2, s2, 0x100
	s_addc_u32 s3, s3, 0
	s_add_u32 s51, s51, 0x100
	s_addc_u32 s52, s52, 0
	s_setprio 1
	v_mfma_f32_16x16x32_bf16 v[40:43], v[162:165], v[178:181], v[40:43]
	v_mfma_f32_16x16x32_bf16 v[36:39], v[170:173], v[178:181], v[36:39]
	v_mfma_f32_16x16x32_bf16 v[28:31], v[162:165], v[186:189], v[28:31]
	v_mfma_f32_16x16x32_bf16 v[24:27], v[170:173], v[186:189], v[24:27]
	v_mfma_f32_16x16x32_bf16 v[16:19], v[162:165], v[194:197], v[16:19]
	v_mfma_f32_16x16x32_bf16 v[12:15], v[170:173], v[194:197], v[12:15]
	v_mfma_f32_16x16x32_bf16 v[4:7], v[162:165], v[202:205], v[4:7]
	v_mfma_f32_16x16x32_bf16 v[0:3], v[170:173], v[202:205], v[0:3]
	v_mfma_f32_16x16x32_bf16 v[40:43], v[166:169], v[182:185], v[40:43]
	v_mfma_f32_16x16x32_bf16 v[36:39], v[174:177], v[182:185], v[36:39]
	v_mfma_f32_16x16x32_bf16 v[28:31], v[166:169], v[190:193], v[28:31]
	v_mfma_f32_16x16x32_bf16 v[24:27], v[174:177], v[190:193], v[24:27]
	v_mfma_f32_16x16x32_bf16 v[16:19], v[166:169], v[198:201], v[16:19]
	v_mfma_f32_16x16x32_bf16 v[12:15], v[174:177], v[198:201], v[12:15]
	v_mfma_f32_16x16x32_bf16 v[4:7], v[166:169], v[206:209], v[4:7]
	v_mfma_f32_16x16x32_bf16 v[0:3], v[174:177], v[206:209], v[0:3]
	s_setprio 0
	s_barrier
	s_cmp_gt_u32 s53, 13
	s_cbranch_scc0 .LBB0_1381
	s_and_b64 vcc, exec, s[10:11]
	s_cbranch_vccz .LBB0_1384
	s_barrier
